# down-proj GEMM: the 40 last-round tiles are split in two K halves on 80 workgroups; second half adds into x after the first (flag + write-through x accesses)
# speedup vs baseline: 1.0002x; 1.0002x over previous
; template <int EPI>
; __device__ __forceinline__ void gemm_tile(const bf16_t* __restrict__ A, const int lda, const bf16_t* __restrict__ Bt, const int ldb,
;                                           const int K, const int m0, const int n0, void* Cout, const int ldc, char* lds, const int tid) {
;     ...
;   const int nt = K >> 6;
;   const int st_row = tid >> 3, st_c = (tid & 7) ^ ((tid >> 4) & 7);
;   auto stageA = [&](int kt, int buf) {
; #pragma unroll
;     for (int i = 0; i < 4; ++i) {
;       const int off = tid * 16 + i * 4096, r = st_row + i * 32;
;       const bf16_t* ga = A + (size_t)(m0 + r) * lda + kt * 64 + st_c * 8;
;       __builtin_amdgcn_global_load_lds((const unsigned*)ga, (__attribute__((address_space(3))) unsigned*)(lds + buf * 32768 + off), 16, 0, 0);
;     }
;   };
;   auto stageB = [&](int kt, int buf) {
; #pragma unroll
;     for (int i = 0; i < 4; ++i) {
;       const int off = tid * 16 + i * 4096, r = st_row + i * 32;
;       const bf16_t* gb = Bt + (size_t)(n0 + r) * ldb + kt * 64 + st_c * 8;
;       __builtin_amdgcn_global_load_lds((const unsigned*)gb, (__attribute__((address_space(3))) unsigned*)(lds + buf * 32768 + 16384 + off), 16, 0, 0);
;     }
;   };
;   auto stage = [&](int kt, int buf) { stageA(kt, buf); stageB(kt, buf); };
;   const int fsw = (fr >> 1) & 7;
;   const int xk0 = (fq ^ fsw) << 4, xk1 = ((4 + fq) ^ fsw) << 4;
;   stage(0, 0);
; template <int EPI>
; __device__ __forceinline__ void gemm_phase(const bf16_t* A, int lda, const bf16_t* Bt, int ldb, int K, int ntn, void* C, int ldc, char* lds, int bid, int nb, const int tid) {
;   constexpr int GM = 4, nM = MT / 128;
;   const int ntiles = nM * ntn, nig = GM * ntn;
;   const int pos = (EPI != EPI_SWIGLU && (nb & 7) == 0) ? (bid & 7) * (nb >> 3) + (bid >> 3) : bid;
;   for (int L = pos; L < ntiles; L += nb) {
;     int mt, nn;
;     if (EPI == EPI_SWIGLU) { mt = L / ntn; nn = L % ntn; }
;     else { const int gid = L / nig, fm = gid * GM, gsz = min(nM - fm, GM), rem = L - gid * nig; mt = fm + rem % gsz; nn = rem / gsz; }
;     gemm_tile<EPI>(A, lda, Bt, ldb, K, mt * 128, nn * 128, C, ldc, lds, tid);
.LBB0_102:
	s_mov_b32 s84, 0
	s_waitcnt vmcnt(2)
	v_lshrrev_b32_e32 v5, 4, v130
	s_mul_i32 s25, s66, 0x580000
	v_readlane_b32 s2, v253, 27
	v_xor_b32_e32 v0, v5, v130
	v_bfe_u32 v1, v130, 1, 3
	s_mul_hi_i32 s23, s66, 0x580000
	s_add_u32 s2, s2, s25
	v_readlane_b32 s3, v253, 28
	s_waitcnt vmcnt(1)
	v_bfe_u32 v8, v130, 4, 2
	v_bitop3_b32 v2, v5, v1, 3 bitop3:0x6c
	v_lshlrev_b32_e32 v0, 4, v0
	v_readlane_b32 s26, v253, 23
	s_addc_u32 s3, s3, s23
	v_and_b32_e32 v7, 15, v130
	v_lshlrev_b32_e32 v174, 4, v2
	v_bitop3_b32 v1, v8, v1, 4 bitop3:0x36
	v_and_b32_e32 v2, 0x70, v0
	v_readlane_b32 s27, v253, 24
	v_bfe_u32 v4, v130, 6, 1
	v_ashrrev_i32_e32 v6, 7, v130
	v_lshlrev_b32_e32 v175, 4, v1
	v_lshl_add_u64 v[0:1], s[26:27], 0, v[2:3]
	v_lshl_add_u64 v[132:133], s[2:3], 0, v[2:3]
	v_lshlrev_b32_e32 v2, 7, v7
	v_readlane_b32 s2, v253, 59
	v_lshl_or_b32 v180, v4, 13, v2
	v_lshl_or_b32 v181, v6, 13, v2
	v_bitop3_b32 v2, v5, 7, v130 bitop3:0x48
	s_add_u32 s2, s2, s25
	v_readlane_b32 s3, v253, 60
	v_lshlrev_b32_e32 v2, 4, v2
	s_addc_u32 s3, s3, s23
	v_lshl_add_u64 v[134:135], s[2:3], 0, v[2:3]
	v_readlane_b32 s2, v253, 61
	v_ashrrev_i32_e32 v131, 3, v130
	v_lshlrev_b32_e32 v176, 4, v130
	v_lshl_or_b32 v182, v6, 6, v7
	v_lshlrev_b32_e32 v4, 6, v4
	v_lshlrev_b32_e32 v6, 2, v8
	v_readlane_b32 s3, v253, 62
	v_add_u32_e32 v177, 32, v131
	v_add_u32_e32 v178, 64, v131
	v_add_u32_e32 v179, 0x60, v131
	v_lshl_add_u64 v[136:137], s[2:3], 0, v[2:3]
	v_add_u32_e32 v183, 0x1000, v176
	v_add_u32_e32 v184, 0x2000, v176
	v_add_u32_e32 v185, 0x3000, v176
	v_add_u32_e32 v186, 0x4000, v176
	v_add_u32_e32 v187, 0x5000, v176
	v_add_u32_e32 v188, 0x6000, v176
	v_add_u32_e32 v189, 0x7000, v176
	v_lshlrev_b32_e32 v2, 2, v4
	v_lshlrev_b32_e32 v138, 2, v6
.LBB0_103:
	s_mov_b32 s60, s84
	s_mov_b64 s[62:63], 0
	s_movk_i32 s80, 0x1580
	s_cmp_eq_u32 s60, 0
	s_cbranch_scc1 .Lsk_top_done
	s_movk_i32 s80, 0xa80
	s_cmp_eq_u32 s60, 1
	s_cbranch_scc1 .Lsk_top_done
	s_movk_i32 s62, 0xb00
	s_movk_i32 s80, 0x1580
.Lsk_top_done:
	v_readlane_b32 s82, v252, 0
	v_readlane_b32 s83, v252, 1
	s_lshl_b32 s43, s66, 6
	s_add_i32 s43, s43, s24
	s_addk_i32 s43, 0x2400
	s_lshl_b32 s43, s43, 2
	s_add_u32 s82, s82, s43
	s_addc_u32 s83, s83, 0
	v_lshl_add_u64 v[214:215], v[0:1], 0, s[62:63]
	v_lshl_add_u64 v[216:217], v[132:133], 0, s[62:63]
	s_ashr_i32 s2, s24, 31
	s_lshr_b32 s2, s2, 27
	s_add_i32 s2, s24, s2
	s_ashr_i32 s3, s2, 5
	s_lshl_b32 s3, s3, 2
	s_sub_i32 s23, 0x85, s3
	s_min_u32 s23, s23, 4
	v_cvt_f32_ubyte0_e32 v4, s23
	v_rcp_iflag_f32_e32 v4, v4
	s_sub_i32 s29, 0, s23
	s_andn2_b32 s2, s2, 31
	s_sub_i32 s2, s24, s2
	v_mul_f32_e32 v4, 0x4f7ffffe, v4
	v_cvt_u32_f32_e32 v4, v4
	s_abs_i32 s27, s2
	s_ashr_i32 s25, s2, 31
	s_mov_b32 s26, 0
	v_readfirstlane_b32 s34, v4
	s_mul_i32 s29, s29, s34
	s_mul_hi_u32 s29, s34, s29
	s_add_i32 s34, s34, s29
	s_mul_hi_u32 s29, s27, s34
	s_mul_i32 s34, s29, s23
	s_sub_i32 s27, s27, s34
	s_add_i32 s34, s29, 1
	s_sub_i32 s35, s27, s23
	s_cmp_ge_u32 s27, s23
	s_cselect_b32 s29, s34, s29
	s_cselect_b32 s27, s35, s27
	s_add_i32 s34, s29, 1
	s_cmp_ge_u32 s27, s23
	s_cselect_b32 s27, s34, s29
	s_xor_b32 s27, s27, s25
	s_sub_i32 s25, s27, s25
	s_mul_i32 s23, s25, s23
	s_sub_i32 s2, s2, s23
	s_add_i32 s3, s3, s2
	s_lshl_b32 s3, s3, 7
	s_lshl_b32 s2, s25, 7
	v_add_u32_e32 v6, s3, v131
	s_movk_i32 s25, 0x1600
	v_readfirstlane_b32 s23, v176
	v_mad_i64_i32 v[4:5], s[34:35], v6, s25, v[214:215]
	s_mov_b32 m0, s23
	v_add_u32_e32 v7, s3, v177
	v_readfirstlane_b32 s23, v183
	global_load_lds_dwordx4 v[4:5], off
	v_mad_i64_i32 v[4:5], s[34:35], v7, s25, v[214:215]
	s_mov_b32 m0, s23
	v_add_u32_e32 v8, s3, v178
	v_readfirstlane_b32 s23, v184
	global_load_lds_dwordx4 v[4:5], off
	v_mad_i64_i32 v[4:5], s[34:35], v8, s25, v[214:215]
	s_mov_b32 m0, s23
	v_add_u32_e32 v9, s3, v179
	v_readfirstlane_b32 s23, v185
	global_load_lds_dwordx4 v[4:5], off
	v_mad_i64_i32 v[4:5], s[34:35], v9, s25, v[214:215]
	s_mov_b32 m0, s23
	v_add_u32_e32 v10, s2, v131
	v_readfirstlane_b32 s23, v186
	global_load_lds_dwordx4 v[4:5], off
	v_mad_i64_i32 v[4:5], s[34:35], v10, s25, v[216:217]
	s_mov_b32 m0, s23
	v_add_u32_e32 v11, s2, v177
	v_readfirstlane_b32 s23, v187
	global_load_lds_dwordx4 v[4:5], off
	v_mad_i64_i32 v[4:5], s[34:35], v11, s25, v[216:217]
	s_mov_b32 m0, s23
	v_add_u32_e32 v12, s2, v178
	v_readfirstlane_b32 s23, v188
	global_load_lds_dwordx4 v[4:5], off
	v_mad_i64_i32 v[4:5], s[34:35], v12, s25, v[216:217]
	s_mov_b32 m0, s23
	v_add_u32_e32 v13, s2, v179
	v_readfirstlane_b32 s23, v189
	global_load_lds_dwordx4 v[4:5], off
	v_mad_i64_i32 v[4:5], s[34:35], v13, s25, v[216:217]
	s_mov_b32 m0, s23
	v_mad_i64_i32 v[140:141], s[34:35], v10, s25, v[134:135]
	global_load_lds_dwordx4 v[4:5], off
	v_mad_i64_i32 v[142:143], s[34:35], v11, s25, v[134:135]
	v_mad_i64_i32 v[144:145], s[34:35], v12, s25, v[134:135]
	v_mad_i64_i32 v[146:147], s[34:35], v13, s25, v[134:135]
	v_mad_i64_i32 v[148:149], s[34:35], v6, s25, v[136:137]
	v_mad_i64_i32 v[150:151], s[34:35], v7, s25, v[136:137]
	v_mad_i64_i32 v[152:153], s[34:35], v8, s25, v[136:137]
	v_mad_i64_i32 v[154:155], s[34:35], v9, s25, v[136:137]
	v_mov_b32_e32 v4, 0
	s_mov_b64 s[34:35], s[62:63]
	v_mov_b32_e32 v5, v4
	v_mov_b32_e32 v6, v4
	v_mov_b32_e32 v7, v4
	v_mov_b32_e32 v12, v4
	v_mov_b32_e32 v13, v4
	v_mov_b32_e32 v14, v4
	v_mov_b32_e32 v15, v4
	s_waitcnt vmcnt(0)
	v_mov_b32_e32 v40, v4
	v_mov_b32_e32 v41, v4
	v_mov_b32_e32 v42, v4
	v_mov_b32_e32 v43, v4
	v_mov_b32_e32 v44, v4
	v_mov_b32_e32 v45, v4
	v_mov_b32_e32 v46, v4
	v_mov_b32_e32 v47, v4
	v_mov_b32_e32 v48, v4
	v_mov_b32_e32 v49, v4
	v_mov_b32_e32 v50, v4
	v_mov_b32_e32 v51, v4
	v_mov_b32_e32 v32, v4
	v_mov_b32_e32 v33, v4
	v_mov_b32_e32 v34, v4
	v_mov_b32_e32 v35, v4
	v_mov_b32_e32 v16, v4
	v_mov_b32_e32 v17, v4
	v_mov_b32_e32 v18, v4
	v_mov_b32_e32 v19, v4
	v_mov_b32_e32 v8, v4
	v_mov_b32_e32 v9, v4
	v_mov_b32_e32 v10, v4
	v_mov_b32_e32 v11, v4
	v_mov_b32_e32 v24, v4
	v_mov_b32_e32 v25, v4
	v_mov_b32_e32 v26, v4
	v_mov_b32_e32 v27, v4
	v_mov_b32_e32 v20, v4
	v_mov_b32_e32 v21, v4
	v_mov_b32_e32 v22, v4
	v_mov_b32_e32 v23, v4
	v_mov_b32_e32 v28, v4
	v_mov_b32_e32 v29, v4
	v_mov_b32_e32 v30, v4
	v_mov_b32_e32 v31, v4
	v_mov_b32_e32 v36, v4
	v_mov_b32_e32 v37, v4
	v_mov_b32_e32 v38, v4
	v_mov_b32_e32 v39, v4
	v_mov_b32_e32 v52, v4
	v_mov_b32_e32 v53, v4
	v_mov_b32_e32 v54, v4
	v_mov_b32_e32 v55, v4
	v_mov_b32_e32 v56, v4
	v_mov_b32_e32 v57, v4
	v_mov_b32_e32 v58, v4
	v_mov_b32_e32 v59, v4
	v_mov_b32_e32 v60, v4
	v_mov_b32_e32 v61, v4
	v_mov_b32_e32 v62, v4
	v_mov_b32_e32 v63, v4
	v_mov_b32_e32 v64, v4
	v_mov_b32_e32 v65, v4
	v_mov_b32_e32 v66, v4
	v_mov_b32_e32 v67, v4
; template <int EPI>
; __device__ __forceinline__ void gemm_tile(const bf16_t* __restrict__ A, const int lda, const bf16_t* __restrict__ Bt, const int ldb,
;                                           const int K, const int m0, const int n0, void* Cout, const int ldc, char* lds, const int tid) {
;     ...
;   for (int kt = 0; kt < nt; ++kt) {
;     asm volatile("s_waitcnt vmcnt(0)" ::: "memory");
;     __syncthreads();
;     if (kt + 1 < nt) stageB(kt + 1, (kt + 1) & 1);
;     const char* sa = lds + (kt & 1) * 32768;
;     const char* sb = sa + 16384;
;     bf16x8 af[2][4], bfr[2][4];
; #pragma unroll
;     for (int ks = 0; ks < 2; ++ks) {
; #pragma unroll
;       for (int m = 0; m < 4; ++m) af[ks][m] = *(const bf16x8*)(sa + (wr * 64 + m * 16 + fr) * 128 + (ks ? xk1 : xk0));
; #pragma unroll
;       for (int n = 0; n < 4; ++n) bfr[ks][n] = *(const bf16x8*)(sb + (wc * 64 + n * 16 + fr) * 128 + (ks ? xk1 : xk0));
;     }
;     if (kt + 1 < nt) stageA(kt + 1, (kt + 1) & 1);
; #pragma unroll
;     for (int ks = 0; ks < 2; ++ks)
; #pragma unroll
;       for (int m = 0; m < 4; ++m)
; #pragma unroll
;         for (int n = 0; n < 4; ++n) acc[m][n] = __builtin_amdgcn_mfma_f32_16x16x32_bf16(bfr[ks][n], af[ks][m], acc[m][n], 0, 0, 0);
;   }
; template <int EPI>
; __device__ __forceinline__ void gemm_phase(const bf16_t* A, int lda, const bf16_t* Bt, int ldb, int K, int ntn, void* C, int ldc, char* lds, int bid, int nb, const int tid) {
;     ...
;   for (int L = pos; L < ntiles; L += nb) {
;     int mt, nn;
;     if (EPI == EPI_SWIGLU) { mt = L / ntn; nn = L % ntn; }
;     else { const int gid = L / nig, fm = gid * GM, gsz = min(nM - fm, GM), rem = L - gid * nig; mt = fm + rem % gsz; nn = rem / gsz; }
;     gemm_tile<EPI>(A, lda, Bt, ldb, K, mt * 128, nn * 128, C, ldc, lds, tid);
.LBB0_104:
	s_add_i32 s25, s26, 0x8000
	s_and_b32 s23, s25, 0x8000
	v_add_u32_e32 v139, s23, v176
	v_add_u32_e32 v70, 0x4000, v139
	v_lshl_add_u64 v[68:69], v[140:141], 0, s[34:35]
	v_readfirstlane_b32 s27, v70
	v_add_u32_e32 v70, 0x5000, v139
	s_mov_b32 m0, s27
	v_readfirstlane_b32 s27, v70
	v_add_u32_e32 v70, 0x6000, v139
	s_waitcnt vmcnt(0)
	s_waitcnt vmcnt(0) lgkmcnt(0)
	s_barrier
	global_load_lds_dwordx4 v[68:69], off
	v_lshl_add_u64 v[68:69], v[142:143], 0, s[34:35]
	s_mov_b32 m0, s27
	v_readfirstlane_b32 s27, v70
	v_add_u32_e32 v70, 0x7000, v139
	global_load_lds_dwordx4 v[68:69], off
	v_lshl_add_u64 v[68:69], v[144:145], 0, s[34:35]
	s_mov_b32 m0, s27
	v_readfirstlane_b32 s27, v70
	global_load_lds_dwordx4 v[68:69], off
	v_lshl_add_u64 v[68:69], v[146:147], 0, s[34:35]
	s_mov_b32 m0, s27
	s_and_b32 s26, s26, 0x8000
	global_load_lds_dwordx4 v[68:69], off
	v_or_b32_e32 v68, s26, v174
	v_add_u32_e32 v69, v68, v181
	v_add_u32_e32 v68, v68, v180
	v_or_b32_e32 v72, s26, v175
	v_readfirstlane_b32 s26, v139
	v_add_u32_e32 v168, 0x1000, v139
	ds_read_b128 v[104:107], v69
	ds_read_b128 v[100:103], v69 offset:2048
	ds_read_b128 v[96:99], v69 offset:4096
	ds_read_b128 v[84:87], v69 offset:6144
	ds_read_b128 v[190:193], v68 offset:16384
	ds_read_b128 v[194:197], v68 offset:18432
	ds_read_b128 v[198:201], v68 offset:20480
	ds_read_b128 v[202:205], v68 offset:22528
	v_add_u32_e32 v68, v72, v181
	v_add_u32_e32 v76, v72, v180
	v_lshl_add_u64 v[158:159], v[148:149], 0, s[34:35]
	s_mov_b32 m0, s26
	v_readfirstlane_b32 s26, v168
	v_add_u32_e32 v168, 0x2000, v139
	ds_read_b128 v[206:209], v68
	ds_read_b128 v[210:213], v68 offset:2048
	ds_read_b128 v[92:95], v68 offset:4096
	ds_read_b128 v[68:71], v68 offset:6144
	ds_read_b128 v[88:91], v76 offset:16384
	ds_read_b128 v[80:83], v76 offset:18432
	ds_read_b128 v[72:75], v76 offset:20480
	ds_read_b128 v[76:79], v76 offset:22528
	global_load_lds_dwordx4 v[158:159], off
	v_lshl_add_u64 v[158:159], v[150:151], 0, s[34:35]
	s_mov_b32 m0, s26
	v_readfirstlane_b32 s26, v168
	v_add_u32_e32 v139, 0x3000, v139
	global_load_lds_dwordx4 v[158:159], off
	v_lshl_add_u64 v[158:159], v[152:153], 0, s[34:35]
	s_mov_b32 m0, s26
	v_readfirstlane_b32 s26, v139
	global_load_lds_dwordx4 v[158:159], off
	v_lshl_add_u64 v[158:159], v[154:155], 0, s[34:35]
	s_mov_b32 m0, s26
	s_waitcnt lgkmcnt(0)
	v_mfma_f32_16x16x32_bf16 v[64:67], v[190:193], v[104:107], v[64:67]
	global_load_lds_dwordx4 v[158:159], off
	s_add_u32 s34, s34, 0x80
	v_mfma_f32_16x16x32_bf16 v[60:63], v[194:197], v[104:107], v[60:63]
	s_addc_u32 s35, s35, 0
	s_cmp_eq_u32 s34, s80
	s_mov_b32 s26, s25
	v_mfma_f32_16x16x32_bf16 v[56:59], v[198:201], v[104:107], v[56:59]
	v_mfma_f32_16x16x32_bf16 v[52:55], v[202:205], v[104:107], v[52:55]
	v_mfma_f32_16x16x32_bf16 v[36:39], v[190:193], v[100:103], v[36:39]
	v_mfma_f32_16x16x32_bf16 v[28:31], v[194:197], v[100:103], v[28:31]
	v_mfma_f32_16x16x32_bf16 v[20:23], v[198:201], v[100:103], v[20:23]
	v_mfma_f32_16x16x32_bf16 v[24:27], v[202:205], v[100:103], v[24:27]
	v_mfma_f32_16x16x32_bf16 v[8:11], v[190:193], v[96:99], v[8:11]
	v_mfma_f32_16x16x32_bf16 v[16:19], v[194:197], v[96:99], v[16:19]
	v_mfma_f32_16x16x32_bf16 v[32:35], v[198:201], v[96:99], v[32:35]
	v_mfma_f32_16x16x32_bf16 v[48:51], v[202:205], v[96:99], v[48:51]
	v_mfma_f32_16x16x32_bf16 v[44:47], v[190:193], v[84:87], v[44:47]
	v_mfma_f32_16x16x32_bf16 v[40:43], v[194:197], v[84:87], v[40:43]
	v_mfma_f32_16x16x32_bf16 v[12:15], v[198:201], v[84:87], v[12:15]
	v_mfma_f32_16x16x32_bf16 v[4:7], v[202:205], v[84:87], v[4:7]
	v_mfma_f32_16x16x32_bf16 v[64:67], v[88:91], v[206:209], v[64:67]
	v_mfma_f32_16x16x32_bf16 v[60:63], v[80:83], v[206:209], v[60:63]
	v_mfma_f32_16x16x32_bf16 v[56:59], v[72:75], v[206:209], v[56:59]
	v_mfma_f32_16x16x32_bf16 v[52:55], v[76:79], v[206:209], v[52:55]
	v_mfma_f32_16x16x32_bf16 v[36:39], v[88:91], v[210:213], v[36:39]
	v_mfma_f32_16x16x32_bf16 v[28:31], v[80:83], v[210:213], v[28:31]
	v_mfma_f32_16x16x32_bf16 v[20:23], v[72:75], v[210:213], v[20:23]
	v_mfma_f32_16x16x32_bf16 v[24:27], v[76:79], v[210:213], v[24:27]
	v_mfma_f32_16x16x32_bf16 v[8:11], v[88:91], v[92:95], v[8:11]
	v_mfma_f32_16x16x32_bf16 v[16:19], v[80:83], v[92:95], v[16:19]
	v_mfma_f32_16x16x32_bf16 v[32:35], v[72:75], v[92:95], v[32:35]
	v_mfma_f32_16x16x32_bf16 v[48:51], v[76:79], v[92:95], v[48:51]
	v_mfma_f32_16x16x32_bf16 v[44:47], v[88:91], v[68:71], v[44:47]
	v_mfma_f32_16x16x32_bf16 v[40:43], v[80:83], v[68:71], v[40:43]
	v_mfma_f32_16x16x32_bf16 v[12:15], v[72:75], v[68:71], v[12:15]
	v_mfma_f32_16x16x32_bf16 v[4:7], v[76:79], v[68:71], v[4:7]
	s_cbranch_scc0 .LBB0_104
	v_add_u32_e32 v84, s23, v174
	v_add_u32_e32 v80, v84, v181
	s_waitcnt vmcnt(0)
	s_waitcnt vmcnt(0) lgkmcnt(0)
	s_barrier
	ds_read_b128 v[68:71], v80
	ds_read_b128 v[72:75], v80 offset:2048
	ds_read_b128 v[76:79], v80 offset:4096
	ds_read_b128 v[80:83], v80 offset:6144
	v_add_u32_e32 v96, v84, v180
	ds_read_b128 v[84:87], v96 offset:16384
	ds_read_b128 v[88:91], v96 offset:18432
	ds_read_b128 v[92:95], v96 offset:20480
	ds_read_b128 v[96:99], v96 offset:22528
	v_add_u32_e32 v139, s23, v175
	v_add_u32_e32 v144, v139, v181
	s_waitcnt lgkmcnt(3)
	v_mfma_f32_16x16x32_bf16 v[36:39], v[84:87], v[72:75], v[36:39]
	ds_read_b128 v[100:103], v144
	ds_read_b128 v[104:107], v144 offset:2048
	ds_read_b128 v[140:143], v144 offset:4096
	ds_read_b128 v[144:147], v144 offset:6144
	v_add_u32_e32 v139, v139, v180
	ds_read_b128 v[148:151], v139 offset:16384
	ds_read_b128 v[152:155], v139 offset:18432
	ds_read_b128 v[190:193], v139 offset:20480
	ds_read_b128 v[194:197], v139 offset:22528
	v_mfma_f32_16x16x32_bf16 v[64:67], v[84:87], v[68:71], v[64:67]
	v_readlane_b32 s26, v253, 25
	v_readlane_b32 s27, v253, 26
	v_mov_b32_e32 v139, v3
	s_waitcnt lgkmcnt(10)
	v_mfma_f32_16x16x32_bf16 v[60:63], v[88:91], v[68:71], v[60:63]
	s_add_i32 s24, s24, s0
	s_mov_b32 s84, 0
	s_cmpk_lg_i32 s0, 0x200
	s_cbranch_scc1 .Ltail_skip_1
	s_cmpk_lt_i32 s24, 0x400
	s_cbranch_scc1 .Ltail_skip_1
	s_cmpk_ge_i32 s24, 0x600
	s_cbranch_scc1 .Ltail_skip_1
	v_readlane_b32 s24, v254, 61
	s_nop 3
	s_and_b32 s84, s24, 1
	s_add_i32 s84, s84, 1
	s_lshr_b32 s24, s24, 1
	s_addk_i32 s24, 0x400
; template <int EPI>
; __device__ __forceinline__ void gemm_tile(const bf16_t* __restrict__ A, const int lda, const bf16_t* __restrict__ Bt, const int ldb,
;                                           const int K, const int m0, const int n0, void* Cout, const int ldc, char* lds, const int tid) {
;     ...
; #pragma unroll
;     for (int ks = 0; ks < 2; ++ks)
; #pragma unroll
;       for (int m = 0; m < 4; ++m)
; #pragma unroll
;         for (int n = 0; n < 4; ++n) acc[m][n] = __builtin_amdgcn_mfma_f32_16x16x32_bf16(bfr[ks][n], af[ks][m], acc[m][n], 0, 0, 0);
;   }
;   if (EPI == EPI_RESID) {
;     float* C0 = (float*)Cout + (size_t)(m0 + wr * 64 + fr) * ldc + n0 + wc * 64 + fq * 4;
; #pragma unroll
;     for (int mh = 0; mh < 2; ++mh) {
;       f32x4 xin[2][4];
; #pragma unroll
;       for (int m = 0; m < 2; ++m)
; #pragma unroll
;         for (int n = 0; n < 4; ++n) xin[m][n] = *(const f32x4*)(C0 + (size_t)(mh * 2 + m) * 16 * ldc + n * 16);
; #pragma unroll
;       for (int m = 0; m < 2; ++m)
; #pragma unroll
;         for (int n = 0; n < 4; ++n) asm volatile("" : "+v"(xin[m][n]));
; #pragma unroll
;       for (int m = 0; m < 2; ++m)
; #pragma unroll
;         for (int n = 0; n < 4; ++n) *(f32x4*)(C0 + (size_t)(mh * 2 + m) * 16 * ldc + n * 16) = xin[m][n] * ALPHA + acc[mh * 2 + m][n];
;     }
;     return;
.Ltail_skip_1:
	s_waitcnt lgkmcnt(9)
	v_mfma_f32_16x16x32_bf16 v[56:59], v[92:95], v[68:71], v[56:59]
	s_waitcnt lgkmcnt(8)
	v_mfma_f32_16x16x32_bf16 v[52:55], v[96:99], v[68:71], v[52:55]
	v_mfma_f32_16x16x32_bf16 v[8:11], v[84:87], v[76:79], v[8:11]
	v_mfma_f32_16x16x32_bf16 v[16:19], v[88:91], v[76:79], v[16:19]
	v_mfma_f32_16x16x32_bf16 v[68:71], v[92:95], v[76:79], v[32:35]
	v_mfma_f32_16x16x32_bf16 v[48:51], v[96:99], v[76:79], v[48:51]
	s_waitcnt lgkmcnt(3)
	v_mfma_f32_16x16x32_bf16 v[76:79], v[148:151], v[104:107], v[36:39]
	s_nop 2
	v_add_u32_e32 v36, s3, v182
	v_ashrrev_i32_e32 v37, 31, v36
	v_lshlrev_b64 v[36:37], 12, v[36:37]
	v_mfma_f32_16x16x32_bf16 v[20:23], v[92:95], v[72:75], v[20:23]
	v_lshl_add_u64 v[36:37], s[26:27], 0, v[36:37]
	s_ashr_i32 s3, s2, 31
	v_lshl_add_u64 v[36:37], s[2:3], 2, v[36:37]
	v_mfma_f32_16x16x32_bf16 v[28:31], v[88:91], v[72:75], v[28:31]
	v_lshl_add_u64 v[36:37], v[36:37], 0, v[2:3]
	v_lshl_add_u64 v[36:37], v[36:37], 0, v[138:139]
	s_mov_b32 s2, 0x10000
	v_mfma_f32_16x16x32_bf16 v[24:27], v[96:99], v[72:75], v[24:27]
	s_cmpk_gt_i32 s24, 0x427
	v_mfma_f32_16x16x32_bf16 v[44:47], v[84:87], v[80:83], v[44:47]
	v_mfma_f32_16x16x32_bf16 v[40:43], v[88:91], v[80:83], v[40:43]
	v_mfma_f32_16x16x32_bf16 v[72:75], v[92:95], v[80:83], v[12:15]
	s_waitcnt lgkmcnt(1)
	v_mfma_f32_16x16x32_bf16 v[84:87], v[190:193], v[104:107], v[20:23]
	s_waitcnt lgkmcnt(0)
	v_mfma_f32_16x16x32_bf16 v[20:23], v[194:197], v[140:143], v[48:51]
	s_nop 2
	v_add_co_u32_e32 v50, vcc, s2, v36
	v_mfma_f32_16x16x32_bf16 v[4:7], v[96:99], v[80:83], v[4:7]
	s_nop 0
	v_addc_co_u32_e32 v51, vcc, 0, v37, vcc
	s_mov_b32 s2, 0x20000
	v_mfma_f32_16x16x32_bf16 v[64:67], v[148:151], v[100:103], v[64:67]
	v_mfma_f32_16x16x32_bf16 v[60:63], v[152:155], v[100:103], v[60:63]
	v_mfma_f32_16x16x32_bf16 v[56:59], v[190:193], v[100:103], v[56:59]
	v_mfma_f32_16x16x32_bf16 v[52:55], v[194:197], v[100:103], v[52:55]
	v_mfma_f32_16x16x32_bf16 v[80:83], v[152:155], v[104:107], v[28:31]
	v_mfma_f32_16x16x32_bf16 v[88:91], v[194:197], v[104:107], v[24:27]
	v_mfma_f32_16x16x32_bf16 v[32:35], v[148:151], v[140:143], v[8:11]
	v_mfma_f32_16x16x32_bf16 v[28:31], v[152:155], v[140:143], v[16:19]
	v_mfma_f32_16x16x32_bf16 v[24:27], v[190:193], v[140:143], v[68:71]
	v_mfma_f32_16x16x32_bf16 v[16:19], v[148:151], v[144:147], v[44:47]
	v_mfma_f32_16x16x32_bf16 v[12:15], v[152:155], v[144:147], v[40:43]
	s_nop 2
	s_cselect_b32 s81, 1, 0
	s_cmp_lg_u32 s60, 2
	s_cbranch_scc1 .Lsk_go
	s_mov_b64 s[40:41], exec
	s_mov_b64 exec, 1
	s_mov_b32 s42, 0
.Lsk_poll:
	global_load_dword v218, v3, s[82:83] sc0 sc1
	s_waitcnt vmcnt(0)
	v_readfirstlane_b32 s43, v218
	s_add_i32 s42, s42, 1
	s_cmp_lg_u32 s43, 0
	s_cbranch_scc1 .Lsk_polled
	s_cmp_lt_u32 s42, 0x20000
	s_cbranch_scc0 .Lsk_polled
	s_sleep 1
	s_branch .Lsk_poll
.Lsk_polled:
	s_mov_b64 exec, s[40:41]
	s_mov_b32 s78, 1.0
; template <int EPI>
; __device__ __forceinline__ void gemm_tile(const bf16_t* __restrict__ A, const int lda, const bf16_t* __restrict__ Bt, const int ldb,
;                                           const int K, const int m0, const int n0, void* Cout, const int ldc, char* lds, const int tid) {
;     ...
;   if (EPI == EPI_RESID) {
;     float* C0 = (float*)Cout + (size_t)(m0 + wr * 64 + fr) * ldc + n0 + wc * 64 + fq * 4;
; #pragma unroll
;     for (int mh = 0; mh < 2; ++mh) {
;       f32x4 xin[2][4];
; #pragma unroll
;       for (int m = 0; m < 2; ++m)
; #pragma unroll
;         for (int n = 0; n < 4; ++n) xin[m][n] = *(const f32x4*)(C0 + (size_t)(mh * 2 + m) * 16 * ldc + n * 16);
; #pragma unroll
;       for (int m = 0; m < 2; ++m)
; #pragma unroll
;         for (int n = 0; n < 4; ++n) asm volatile("" : "+v"(xin[m][n]));
; #pragma unroll
;       for (int m = 0; m < 2; ++m)
; #pragma unroll
;         for (int n = 0; n < 4; ++n) *(f32x4*)(C0 + (size_t)(mh * 2 + m) * 16 * ldc + n * 16) = xin[m][n] * ALPHA + acc[mh * 2 + m][n];
;     }
;     return;
.Lsk_go:
	global_load_dwordx4 v[38:41], v[36:37], off sc0 sc1
	global_load_dwordx4 v[42:45], v[36:37], off offset:64 sc0 sc1
	global_load_dwordx4 v[46:49], v[36:37], off offset:128 sc0 sc1
	global_load_dwordx4 v[68:71], v[36:37], off offset:192 sc0 sc1
	v_mfma_f32_16x16x32_bf16 v[8:11], v[190:193], v[144:147], v[72:75]
	s_nop 2
	global_load_dwordx4 v[72:75], v[50:51], off sc0 sc1
	global_load_dwordx4 v[92:95], v[50:51], off offset:64 sc0 sc1
	global_load_dwordx4 v[96:99], v[50:51], off offset:128 sc0 sc1
	global_load_dwordx4 v[100:103], v[50:51], off offset:192 sc0 sc1
	s_waitcnt vmcnt(7)
	s_nop 0
	v_pk_fma_f32 v[40:41], v[40:41], s[78:79], v[66:67] op_sel_hi:[1,0,1]
	v_pk_fma_f32 v[38:39], v[38:39], s[78:79], v[64:65] op_sel_hi:[1,0,1]
	s_waitcnt vmcnt(6)
	s_waitcnt vmcnt(5)
	s_waitcnt vmcnt(4)
	s_waitcnt vmcnt(3)
	s_waitcnt vmcnt(2)
	s_waitcnt vmcnt(1)
	s_waitcnt vmcnt(0)
	global_store_dwordx4 v[36:37], v[38:41], off sc0 sc1
	v_mfma_f32_16x16x32_bf16 v[4:7], v[194:197], v[144:147], v[4:7]
	s_nop 0
	v_fma_f32 v40, v44, s78, v62
	v_fma_f32 v41, v45, s78, v63
	v_pk_fma_f32 v[38:39], v[42:43], s[78:79], v[60:61] op_sel_hi:[1,0,1]
	global_store_dwordx4 v[36:37], v[38:41], off offset:64 sc0 sc1
	s_nop 1
	v_pk_fma_f32 v[40:41], v[48:49], s[78:79], v[58:59] op_sel_hi:[1,0,1]
	v_pk_fma_f32 v[38:39], v[46:47], s[78:79], v[56:57] op_sel_hi:[1,0,1]
	global_store_dwordx4 v[36:37], v[38:41], off offset:128 sc0 sc1
	s_nop 1
	v_pk_fma_f32 v[40:41], v[70:71], s[78:79], v[54:55] op_sel_hi:[1,0,1]
	v_pk_fma_f32 v[38:39], v[68:69], s[78:79], v[52:53] op_sel_hi:[1,0,1]
	global_store_dwordx4 v[36:37], v[38:41], off offset:192 sc0 sc1
	v_add_co_u32_e32 v70, vcc, s2, v36
	s_nop 0
	v_pk_fma_f32 v[40:41], v[74:75], s[78:79], v[78:79] op_sel_hi:[1,0,1]
	v_pk_fma_f32 v[38:39], v[72:73], s[78:79], v[76:77] op_sel_hi:[1,0,1]
	global_store_dwordx4 v[50:51], v[38:41], off sc0 sc1
	v_addc_co_u32_e32 v71, vcc, 0, v37, vcc
	s_nop 0
	v_pk_fma_f32 v[40:41], v[94:95], s[78:79], v[82:83] op_sel_hi:[1,0,1]
	v_pk_fma_f32 v[38:39], v[92:93], s[78:79], v[80:81] op_sel_hi:[1,0,1]
	global_store_dwordx4 v[50:51], v[38:41], off offset:64 sc0 sc1
	s_mov_b32 s2, 0x30000
	v_add_co_u32_e32 v36, vcc, s2, v36
	v_pk_fma_f32 v[40:41], v[98:99], s[78:79], v[86:87] op_sel_hi:[1,0,1]
	v_pk_fma_f32 v[38:39], v[96:97], s[78:79], v[84:85] op_sel_hi:[1,0,1]
	global_store_dwordx4 v[50:51], v[38:41], off offset:128 sc0 sc1
	v_addc_co_u32_e32 v37, vcc, 0, v37, vcc
	s_nop 0
	v_pk_fma_f32 v[40:41], v[102:103], s[78:79], v[90:91] op_sel_hi:[1,0,1]
	v_pk_fma_f32 v[38:39], v[100:101], s[78:79], v[88:89] op_sel_hi:[1,0,1]
	global_store_dwordx4 v[50:51], v[38:41], off offset:192 sc0 sc1
	global_load_dwordx4 v[38:41], v[70:71], off sc0 sc1
	s_nop 0
	global_load_dwordx4 v[42:45], v[70:71], off offset:64 sc0 sc1
	global_load_dwordx4 v[46:49], v[70:71], off offset:128 sc0 sc1
	global_load_dwordx4 v[50:53], v[70:71], off offset:192 sc0 sc1
	global_load_dwordx4 v[54:57], v[36:37], off sc0 sc1
	global_load_dwordx4 v[58:61], v[36:37], off offset:64 sc0 sc1
	global_load_dwordx4 v[62:65], v[36:37], off offset:128 sc0 sc1
	global_load_dwordx4 v[66:69], v[36:37], off offset:192 sc0 sc1
	s_waitcnt vmcnt(7)
	s_waitcnt vmcnt(6)
	s_waitcnt vmcnt(5)
	s_waitcnt vmcnt(4)
	s_waitcnt vmcnt(3)
	s_waitcnt vmcnt(2)
	s_waitcnt vmcnt(1)
	s_waitcnt vmcnt(0)
	v_pk_fma_f32 v[34:35], v[40:41], s[78:79], v[34:35] op_sel_hi:[1,0,1]
	v_pk_fma_f32 v[32:33], v[38:39], s[78:79], v[32:33] op_sel_hi:[1,0,1]
	v_pk_fma_f32 v[30:31], v[44:45], s[78:79], v[30:31] op_sel_hi:[1,0,1]
	v_pk_fma_f32 v[28:29], v[42:43], s[78:79], v[28:29] op_sel_hi:[1,0,1]
	v_pk_fma_f32 v[26:27], v[48:49], s[78:79], v[26:27] op_sel_hi:[1,0,1]
	v_pk_fma_f32 v[24:25], v[46:47], s[78:79], v[24:25] op_sel_hi:[1,0,1]
	v_pk_fma_f32 v[22:23], v[52:53], s[78:79], v[22:23] op_sel_hi:[1,0,1]
	v_pk_fma_f32 v[20:21], v[50:51], s[78:79], v[20:21] op_sel_hi:[1,0,1]
	v_pk_fma_f32 v[18:19], v[56:57], s[78:79], v[18:19] op_sel_hi:[1,0,1]
	v_pk_fma_f32 v[16:17], v[54:55], s[78:79], v[16:17] op_sel_hi:[1,0,1]
	v_pk_fma_f32 v[14:15], v[60:61], s[78:79], v[14:15] op_sel_hi:[1,0,1]
	v_pk_fma_f32 v[12:13], v[58:59], s[78:79], v[12:13] op_sel_hi:[1,0,1]
	v_pk_fma_f32 v[10:11], v[64:65], s[78:79], v[10:11] op_sel_hi:[1,0,1]
	v_pk_fma_f32 v[8:9], v[62:63], s[78:79], v[8:9] op_sel_hi:[1,0,1]
	v_pk_fma_f32 v[6:7], v[68:69], s[78:79], v[6:7] op_sel_hi:[1,0,1]
	v_pk_fma_f32 v[4:5], v[66:67], s[78:79], v[4:5] op_sel_hi:[1,0,1]
	global_store_dwordx4 v[70:71], v[32:35], off sc0 sc1
	global_store_dwordx4 v[70:71], v[28:31], off offset:64 sc0 sc1
	global_store_dwordx4 v[70:71], v[24:27], off offset:128 sc0 sc1
	global_store_dwordx4 v[70:71], v[20:23], off offset:192 sc0 sc1
	global_store_dwordx4 v[36:37], v[16:19], off sc0 sc1
	global_store_dwordx4 v[36:37], v[12:15], off offset:64 sc0 sc1
	global_store_dwordx4 v[36:37], v[8:11], off offset:128 sc0 sc1
	global_store_dwordx4 v[36:37], v[4:7], off offset:192 sc0 sc1
	s_cmp_lg_u32 s60, 1
	s_cbranch_scc1 .Lsk_noflag
	s_waitcnt vmcnt(0)
	s_barrier
	v_cmp_eq_u32_e32 vcc, 0, v130
	s_and_saveexec_b64 s[40:41], vcc
	v_mov_b32_e32 v218, 1
	global_store_dword v3, v218, s[82:83] sc0 sc1
	s_mov_b64 exec, s[40:41]
.Lsk_noflag:
	s_mov_b32 s78, 0x3fb504f3
	s_cmp_lg_u32 s81, 0
	s_cbranch_scc0 .LBB0_103
